# attention K/V staging batched at the top of each sub-iteration (loop heads not aligned)
# baseline (speedup 1.0000x reference)
; DI int tid512() { int t = threadIdx.x; asm volatile("" : "+v"(t)); return t; }
; #define A_LOAD(KB) { _Pragma("unroll") for (int i = 0; i < 2; ++i) { rk[i] = *(const u32x4*)(kp + (size_t)((KB) * 64 + 32 * i) * 1024); rv[i] = *(const u32x4*)(vp + (size_t)(64 * i) * TOK + (KB) * 64); } }
; #define A_STORE(STG) { char* D_ = smem + (STG) * ST; _Pragma("unroll") for (int i = 0; i < 2; ++i) { *(u32x4*)(D_ + ksoff + i * 32 * 272) = rk[i]; \
;       u32x2 lo2_ = {rv[i].x, rv[i].y}, hi2_ = {rv[i].z, rv[i].w}; *(u32x2*)(D_ + vsoff + i * 64 * VROW) = lo2_; *(u32x2*)(D_ + vsoff + i * 64 * VROW + 16) = hi2_; } }
; DI void attn_block(const Params& p, int layer, int hd, int q0, int nkeys, char* smem) {
;   constexpr int KT = 64 * 272, VROW = 144, ST = KT + 128 * VROW;
;   const int t = tid512(), lane = t & 63, w = t >> 6, mp = w >> 2, wq = w & 3, r = lane & 31, h = lane >> 5;
;   const bf16_t* DQ = (const bf16_t*)(p.ws + O_DQ);
;   const bf16_t* DK = (const bf16_t*)(p.ws + O_DK);
;   const bf16_t* DVT = (const bf16_t*)(p.ws + O_DVT);
;   const float* scal = (const float*)(p.ws + O_SCAL);
;   const int q = q0 + 32 * wq + r;
;   bf16x8 qf[4];
; #pragma unroll
;   for (int s = 0; s < 4; ++s) qf[s] = *(const bf16x8*)(DQ + (size_t)q * 1024 + hd * 128 + 64 * mp + 16 * s + 8 * h);
;   const int nkb = nkeys >> 6, lastkb = nkb - 1;
;   const bf16_t* kp = DK + (size_t)(t >> 4) * 1024 + hd * 128 + (t & 15) * 8;
;   const int ksoff = (t >> 4) * 272 + (t & 15) * 16;
;   const bf16_t* vp = DVT + (size_t)(hd * 128 + (t >> 3)) * TOK + (t & 7) * 8;
;   const int vsoff = KT + (t >> 3) * VROW + ((t & 7) >> 1) * 32 + (t & 1) * 8;
;   u32x4 rk[2], rv[2];
;     ...
;   A_LOAD(0);
;   __syncthreads();
;   A_STORE(0);
;   A_LOAD(lastkb < 1 ? lastkb : 1);
;   A_STORE(1);
;   A_LOAD(lastkb < 2 ? lastkb : 2);
;   __syncthreads();
;   float m = -1e30f, l = 0.f;
;   f32x16 o[4];
; #pragma unroll
;   for (int vt = 0; vt < 4; ++vt)
; #pragma unroll
;     for (int i = 0; i < 16; ++i) o[vt][i] = 0.f;
;   f32x16 sc[2], sn[2];
;   A_SCORES(sc, 0);
.LBB0_392:
	s_lshl_b32 s4, s6, 7
	v_mov_b32_e32 v202, v0
	s_and_b32 s4, s4, 0x1f80
	s_addk_i32 s4, 0x100
	v_lshrrev_b32_e32 v2, 1, v202
	v_and_b32_e32 v200, 31, v202
	v_and_b32_e32 v201, 0x60, v2
	v_or3_b32 v198, v200, s4, v201
	v_readlane_b32 s4, v254, 9
	v_lshlrev_b32_e32 v180, 11, v198
	v_readlane_b32 s5, v254, 10
	v_ashrrev_i32_e32 v199, 8, v202
	v_lshlrev_b32_e32 v4, 6, v199
	v_lshl_add_u64 v[2:3], s[4:5], 0, v[180:181]
	s_lshl_b32 s4, s6, 1
	s_and_b32 s94, s4, 0x7fffff80
	s_lshl_b32 s22, s94, 1
	v_bfe_u32 v193, v202, 5, 1
	v_lshl_add_u64 v[2:3], v[2:3], 0, s[22:23]
	v_ashrrev_i32_e32 v5, 31, v4
	v_lshl_add_u64 v[2:3], v[4:5], 1, v[2:3]
	v_lshlrev_b32_e32 v180, 4, v193
	v_ashrrev_i32_e32 v34, 4, v202
	v_lshl_add_u64 v[2:3], v[2:3], 0, v[180:181]
	v_ashrrev_i32_e32 v35, 31, v34
	v_readlane_b32 s4, v254, 11
	global_load_dwordx4 v[130:133], v[2:3], off
	global_load_dwordx4 v[134:137], v[2:3], off offset:32
	global_load_dwordx4 v[138:141], v[2:3], off offset:64
	global_load_dwordx4 v[142:145], v[2:3], off offset:96
	v_lshlrev_b64 v[2:3], 11, v[34:35]
	v_readlane_b32 s5, v254, 12
	v_lshlrev_b32_e32 v35, 4, v202
	v_and_b32_e32 v36, 0xf0, v35
	v_lshl_add_u64 v[2:3], s[4:5], 0, v[2:3]
	v_lshl_add_u64 v[2:3], v[2:3], 0, s[22:23]
	v_mov_b32_e32 v37, v181
	v_readlane_b32 s4, v253, 54
	v_lshl_add_u64 v[162:163], v[2:3], 0, v[36:37]
	v_ashrrev_i32_e32 v37, 3, v202
	v_readlane_b32 s5, v253, 55
	v_add_u32_e32 v4, s94, v37
	v_mov_b32_e32 v5, v181
	v_mov_b64_e32 v[2:3], s[4:5]
	v_mad_i64_i32 v[2:3], s[4:5], v4, s29, v[2:3]
	v_and_b32_e32 v4, 7, v202
	v_lshlrev_b32_e32 v4, 4, v4
	v_add_co_u32_e32 v10, vcc, s46, v162
	v_lshl_add_u64 v[164:165], v[2:3], 0, v[4:5]
	s_nop 0
	v_addc_co_u32_e32 v11, vcc, 0, v163, vcc
	v_add_co_u32_e32 v38, vcc, s30, v164
	global_load_dwordx4 v[2:5], v[162:163], off
	global_load_dwordx4 v[6:9], v[164:165], off
	v_addc_co_u32_e32 v39, vcc, 0, v165, vcc
	v_add_co_u32_e32 v18, vcc, s87, v162
	global_load_dwordx4 v[10:13], v[10:11], off
	s_nop 0
	global_load_dwordx4 v[14:17], v[38:39], off
	v_addc_co_u32_e32 v19, vcc, 0, v163, vcc
	v_add_co_u32_e32 v26, vcc, s47, v162
	s_waitcnt vmcnt(63) expcnt(7) lgkmcnt(15)
	s_barrier
	global_load_dwordx4 v[18:21], v[18:19], off
	s_nop 0
	global_load_dwordx4 v[22:25], v[164:165], off offset:128
	v_addc_co_u32_e32 v27, vcc, 0, v163, vcc
	global_load_dwordx4 v[26:29], v[26:27], off
	s_nop 0
	global_load_dwordx4 v[30:33], v[38:39], off offset:128
	v_lshlrev_b32_e32 v40, 3, v202
	v_mul_lo_u32 v37, v37, s28
	s_movk_i32 s4, 0x110
	v_and_b32_e32 v35, 0x60, v35
	v_mad_u64_u32 v[194:195], s[4:5], v34, s4, v[36:37]
	v_and_or_b32 v34, v40, 8, v37
	v_add_u32_e32 v205, v34, v35
	v_add_u32_e32 v36, 16, v194
	v_add_u32_e32 v34, 16, v205
	v_add_u32_e32 v35, 0x4000, v34
	v_add_u32_e32 v37, 0x6800, v34
	v_add_u32_e32 v40, 0xd000, v34
	global_load_dwordx4 v[146:149], v[164:165], off offset:256
	s_mov_b32 s4, 0x50000
	s_mov_b32 s42, 1
	v_mul_u32_u24_e32 v203, 0x90, v200
	v_mov_b32_e32 v204, 0xf149f2ca
	v_mov_b32_e32 v195, 0
	s_waitcnt vmcnt(0)
	ds_write_b128 v36, v[2:5]
	ds_write2_b64 v35, v[6:7], v[8:9] offset0:128 offset1:130
	ds_write_b128 v36, v[10:13] offset:8704
	ds_write2_b64 v37, v[14:15], v[16:17] offset1:2
	ds_write_b128 v36, v[18:21] offset:35840
	ds_write2_b64 v40, v[22:23], v[24:25] offset1:2
	ds_write_b128 v36, v[26:29] offset:44544
	v_add_u32_e32 v2, 0xf000, v34
	ds_write2_b64 v2, v[30:31], v[32:33] offset0:128 offset1:130
	v_add_co_u32_e32 v2, vcc, s84, v162
	global_load_dwordx4 v[150:153], v[38:39], off offset:256
	s_nop 0
	v_addc_co_u32_e32 v3, vcc, 0, v163, vcc
	v_add_co_u32_e32 v4, vcc, s4, v162
	s_mov_b32 s4, 0
	s_nop 0
	v_addc_co_u32_e32 v5, vcc, 0, v163, vcc
	global_load_dwordx4 v[158:161], v[2:3], off
	global_load_dwordx4 v[154:157], v[4:5], off
	v_lshl_add_u32 v2, v199, 7, 16
	v_mul_u32_u24_e32 v3, 0x110, v200
	v_add3_u32 v206, v2, v180, v3
	s_waitcnt lgkmcnt(0)
	s_barrier
	ds_read_b128 v[2:5], v206
	ds_read_b128 v[6:9], v206 offset:32
	s_waitcnt lgkmcnt(1)
	v_mfma_f32_32x32x16_bf16 v[114:129], v[2:5], v[130:133], 0
	s_mov_b32 s18, s4
	s_mov_b32 s19, s4
	s_mov_b32 s5, s4
	s_mov_b32 s6, s4
	s_mov_b32 s7, s4
	s_mov_b32 s8, s4
	s_mov_b32 s9, s4
	s_waitcnt lgkmcnt(0)
	v_mfma_f32_32x32x16_bf16 v[114:129], v[6:9], v[134:137], v[114:129]
	ds_read_b128 v[2:5], v206 offset:64
	ds_read_b128 v[6:9], v206 offset:96
	s_mov_b32 s10, s4
	s_mov_b32 s11, s4
	s_mov_b32 s12, s4
	s_mov_b32 s13, s4
	s_mov_b32 s14, s4
	s_mov_b32 s15, s4
	s_waitcnt lgkmcnt(1)
	v_mfma_f32_32x32x16_bf16 v[114:129], v[2:5], v[138:141], v[114:129]
	ds_read_b128 v[2:5], v206 offset:8704
	ds_read_b128 v[10:13], v206 offset:8736
	s_mov_b32 s16, s4
	s_mov_b32 s17, s4
	v_mov_b64_e32 v[64:65], s[18:19]
	v_mov_b64_e32 v[50:51], s[4:5]
	v_mov_b64_e32 v[62:63], s[16:17]
	v_mov_b64_e32 v[60:61], s[14:15]
	s_waitcnt lgkmcnt(1)
	v_mfma_f32_32x32x16_bf16 v[98:113], v[2:5], v[130:133], 0
	ds_read_b128 v[2:5], v206 offset:8768
	v_mov_b64_e32 v[58:59], s[12:13]
	v_mov_b64_e32 v[56:57], s[10:11]
	v_mov_b64_e32 v[54:55], s[8:9]
	v_mov_b64_e32 v[52:53], s[6:7]
	v_mov_b64_e32 v[18:19], v[50:51]
	v_mov_b64_e32 v[34:35], v[50:51]
	s_waitcnt lgkmcnt(1)
	v_mfma_f32_32x32x16_bf16 v[98:113], v[10:13], v[134:137], v[98:113]
	s_mov_b32 s5, 2
	v_mov_b64_e32 v[20:21], v[52:53]
	v_mov_b64_e32 v[22:23], v[54:55]
	v_mov_b64_e32 v[24:25], v[56:57]
	v_mov_b64_e32 v[26:27], v[58:59]
	v_mov_b64_e32 v[28:29], v[60:61]
	v_mov_b64_e32 v[30:31], v[62:63]
	v_mfma_f32_32x32x16_bf16 v[114:129], v[6:9], v[142:145], v[114:129]
	ds_read_b128 v[6:9], v206 offset:8800
	v_mov_b64_e32 v[32:33], v[64:65]
	v_mov_b64_e32 v[36:37], v[52:53]
	v_mov_b64_e32 v[38:39], v[54:55]
	v_mov_b64_e32 v[40:41], v[56:57]
	v_mov_b64_e32 v[42:43], v[58:59]
	v_mov_b64_e32 v[44:45], v[60:61]
	s_waitcnt lgkmcnt(1)
; DI float ex2(float x) { return __builtin_amdgcn_exp2f(x); }
; #define A_LOAD(KB) { _Pragma("unroll") for (int i = 0; i < 2; ++i) { rk[i] = *(const u32x4*)(kp + (size_t)((KB) * 64 + 32 * i) * 1024); rv[i] = *(const u32x4*)(vp + (size_t)(64 * i) * TOK + (KB) * 64); } }
; #define A_STORE(STG) { char* D_ = smem + (STG) * ST; _Pragma("unroll") for (int i = 0; i < 2; ++i) { *(u32x4*)(D_ + ksoff + i * 32 * 272) = rk[i]; \
;       u32x2 lo2_ = {rv[i].x, rv[i].y}, hi2_ = {rv[i].z, rv[i].w}; *(u32x2*)(D_ + vsoff + i * 64 * VROW) = lo2_; *(u32x2*)(D_ + vsoff + i * 64 * VROW + 16) = hi2_; } }
; #define A_SCORES(DST, STG) { const char* Ks_ = smem + (STG) * ST; _Pragma("unroll") for (int kt = 0; kt < 2; ++kt) { \
;       _Pragma("unroll") for (int i = 0; i < 16; ++i) DST[kt][i] = 0.f; \
;       _Pragma("unroll") for (int s = 0; s < 4; ++s) { const bf16x8 a_ = *(const bf16x8*)(Ks_ + (32 * kt + r) * 272 + 128 * mp + 32 * s + 16 * h); DST[kt] = MFMA32(a_, qf[s], DST[kt]); } } }
; DI void attn_block(const Params& p, int layer, int hd, int q0, int nkeys, char* smem) {
;     ...
;   A_SCORES(sc, 0);
;   int c0 = 0, c1 = 1, c2 = 2;
;   for (int kb = 0; kb < nkb; ++kb) {
;     const char* Vs = smem + c0 * ST + KT;
;     A_STORE(c2);
;     A_LOAD((kb + 3 < lastkb) ? kb + 3 : lastkb);
;     if (kb + 1 < nkb) A_SCORES(sn, c1);
;     float mx = fmaxf(sc[0][0], sc[1][0]);
; #pragma unroll
;     for (int i = 1; i < 16; ++i) mx = fmaxf(mx, fmaxf(sc[0][i], sc[1][i]));
;     {
;       const auto pr_ = __builtin_amdgcn_permlane32_swap(__float_as_uint(mx), __float_as_uint(mx), false, false);
;       mx = fmaxf(__uint_as_float(pr_[0]), __uint_as_float(pr_[1]));
;     }
;     if (__any(mx > m + 8.f)) {
;       const float mn = (mx > m + 8.f) ? mx : m;
;       const float alpha = ex2(m - mn);
;       l *= alpha;
; #pragma unroll
;       for (int vt = 0; vt < 4; ++vt)
; #pragma unroll
;         for (int i = 0; i < 16; ++i) o[vt][i] *= alpha;
;       m = mn;
;     }
	v_mfma_f32_32x32x16_bf16 v[98:113], v[2:5], v[138:141], v[98:113]
	v_mov_b64_e32 v[46:47], v[62:63]
	v_mov_b64_e32 v[48:49], v[64:65]
	s_waitcnt lgkmcnt(0)
	v_mfma_f32_32x32x16_bf16 v[98:113], v[6:9], v[142:145], v[98:113]
	v_mov_b64_e32 v[2:3], v[50:51]
	v_mov_b64_e32 v[4:5], v[52:53]
	v_mov_b64_e32 v[6:7], v[54:55]
	v_mov_b64_e32 v[8:9], v[56:57]
	v_mov_b64_e32 v[10:11], v[58:59]
	v_mov_b64_e32 v[12:13], v[60:61]
	v_mov_b64_e32 v[14:15], v[62:63]
	v_mov_b64_e32 v[16:17], v[64:65]
	v_mov_b32_e32 v196, 0x1a410
	v_lshl_add_u32 v196, v0, 2, v196
	ds_write_b32 v196, v170 offset:0
	ds_write_b32 v196, v171 offset:2048
	ds_write_b32 v196, v172 offset:4096
	ds_write_b32 v196, v173 offset:6144
	ds_write_b32 v196, v174 offset:8192
	ds_write_b32 v196, v175 offset:10240
	ds_write_b32 v196, v176 offset:12288
	ds_write_b32 v196, v177 offset:14336
	s_waitcnt lgkmcnt(0)
	ds_write_b32 v196, v178 offset:16384
	ds_write_b32 v196, v179 offset:18432
	v_readfirstlane_b32 s52, v162
	v_readfirstlane_b32 s53, v163
	v_readfirstlane_b32 s56, v164
	v_readfirstlane_b32 s57, v165
	s_nop 3
	s_add_u32 s54, s52, s46
	s_addc_u32 s55, s53, 0
	s_add_u32 s58, s56, s30
	s_addc_u32 s59, s57, 0
	v_subrev_u32_e32 v175, s52, v162
	v_subrev_u32_e32 v176, s56, v164
	v_add_u32_e32 v162, 0x11800, v206
	v_add3_u32 v163, v203, v180, 16
	v_add_u32_e32 v174, 0x11810, v205
	v_add_u32_e32 v165, 0x11810, v194
	v_add_u32_e32 v164, 0xd000, v163
	s_mov_b32 s6, 0
	s_nop 7
	v_max3_f32 v178, v114, v115, v116
	v_max3_f32 v179, v117, v118, v119
	v_max3_f32 v178, v178, v120, v121
	v_max3_f32 v179, v179, v122, v123
	v_max3_f32 v178, v178, v124, v125
	v_max3_f32 v179, v179, v126, v127
	v_max3_f32 v178, v178, v128, v129
	v_max3_f32 v179, v179, v98, v99
	v_max3_f32 v178, v178, v100, v101
	v_max3_f32 v179, v179, v102, v103
	v_max3_f32 v178, v178, v104, v105
	v_max3_f32 v179, v179, v106, v107
	v_max3_f32 v178, v178, v108, v109
	v_max3_f32 v179, v179, v110, v111
	v_max3_f32 v178, v178, v112, v113
	v_max_f32_e32 v178, v178, v179
	v_mov_b32_e32 v179, v178
	s_nop 1
	v_permlane32_swap_b32_e32 v178, v179
	v_max_f32_e32 v178, v178, v179
	v_sub_f32_e32 v114, v114, v178
	v_sub_f32_e32 v115, v115, v178
	v_sub_f32_e32 v116, v116, v178
	v_sub_f32_e32 v117, v117, v178
	v_sub_f32_e32 v118, v118, v178
	v_sub_f32_e32 v119, v119, v178
	v_sub_f32_e32 v120, v120, v178
	v_sub_f32_e32 v121, v121, v178
	v_sub_f32_e32 v122, v122, v178
	v_sub_f32_e32 v123, v123, v178
	v_sub_f32_e32 v124, v124, v178
	v_sub_f32_e32 v125, v125, v178
	v_sub_f32_e32 v126, v126, v178
	v_sub_f32_e32 v127, v127, v178
	v_sub_f32_e32 v128, v128, v178
	v_sub_f32_e32 v129, v129, v178
	v_sub_f32_e32 v98, v98, v178
	v_sub_f32_e32 v99, v99, v178
	v_sub_f32_e32 v100, v100, v178
	v_sub_f32_e32 v101, v101, v178
	v_sub_f32_e32 v102, v102, v178
	v_sub_f32_e32 v103, v103, v178
	v_sub_f32_e32 v104, v104, v178
	v_sub_f32_e32 v105, v105, v178
	v_sub_f32_e32 v106, v106, v178
	v_sub_f32_e32 v107, v107, v178
	v_sub_f32_e32 v108, v108, v178
	v_sub_f32_e32 v109, v109, v178
	v_sub_f32_e32 v110, v110, v178
	v_sub_f32_e32 v111, v111, v178
	v_sub_f32_e32 v112, v112, v178
	v_sub_f32_e32 v113, v113, v178
	v_mul_f32_e32 v66, -1.0, v178
	v_mov_b32_e32 v197, 0
	v_mov_b32_e32 v207, 0
	v_mov_b32_e32 v67, v66
	v_mov_b32_e32 v68, v66
	v_mov_b32_e32 v69, v66
	v_mov_b32_e32 v70, v66
	v_mov_b32_e32 v71, v66
	v_mov_b32_e32 v72, v66
	v_mov_b32_e32 v73, v66
	v_mov_b32_e32 v74, v66
	v_mov_b32_e32 v75, v66
	v_mov_b32_e32 v76, v66
	v_mov_b32_e32 v77, v66
	v_mov_b32_e32 v78, v66
	v_mov_b32_e32 v79, v66
	v_mov_b32_e32 v80, v66
	v_mov_b32_e32 v81, v66
	s_waitcnt vmcnt(0)
	s_waitcnt lgkmcnt(0)
	ds_read_b128 v[220:223], v163 offset:17408
	ds_read_b128 v[208:211], v206 offset:35840
	ds_read_b128 v[224:227], v163 offset:22016
	ds_read_b128 v[212:215], v206 offset:35872
	ds_read_b128 v[228:231], v163 offset:26624
	ds_read_b128 v[216:219], v206 offset:35904
	ds_read_b128 v[238:241], v163 offset:31232
; #define MFMA32(a, b, c) __builtin_amdgcn_mfma_f32_32x32x16_bf16((a), (b), (c), 0, 0, 0)
; DI float ex2(float x) { return __builtin_amdgcn_exp2f(x); }
; #define A_LOAD(KB) { _Pragma("unroll") for (int i = 0; i < 2; ++i) { rk[i] = *(const u32x4*)(kp + (size_t)((KB) * 64 + 32 * i) * 1024); rv[i] = *(const u32x4*)(vp + (size_t)(64 * i) * TOK + (KB) * 64); } }
; DI void attn_block(const Params& p, int layer, int hd, int q0, int nkeys, char* smem) {
;     ...
;   for (int kb = 0; kb < nkb; ++kb) {
;     const char* Vs = smem + c0 * ST + KT;
;     A_STORE(c2);
;     A_LOAD((kb + 3 < lastkb) ? kb + 3 : lastkb);
;     if (kb + 1 < nkb) A_SCORES(sn, c1);
;     float mx = fmaxf(sc[0][0], sc[1][0]);
; #pragma unroll
;     for (int i = 1; i < 16; ++i) mx = fmaxf(mx, fmaxf(sc[0][i], sc[1][i]));
;     {
;       const auto pr_ = __builtin_amdgcn_permlane32_swap(__float_as_uint(mx), __float_as_uint(mx), false, false);
;       mx = fmaxf(__uint_as_float(pr_[0]), __uint_as_float(pr_[1]));
;     }
;     if (__any(mx > m + 8.f)) {
;       const float mn = (mx > m + 8.f) ? mx : m;
;       const float alpha = ex2(m - mn);
;       l *= alpha;
; #pragma unroll
;       for (int vt = 0; vt < 4; ++vt)
; #pragma unroll
;         for (int i = 0; i < 16; ++i) o[vt][i] *= alpha;
;       m = mn;
;     }
;     bf16x8 va[2][4];
;     const char* vbase = Vs + r * VROW + 16 * h;
; #pragma unroll
;     for (int vt = 0; vt < 4; ++vt) va[0][vt] = *(const bf16x8*)(vbase + 32 * vt * VROW);
;     float ls[4] = {0.f, 0.f, 0.f, 0.f};
; #pragma unroll
;     for (int st = 0; st < 4; ++st) {
;       if (st < 3) {
; #pragma unroll
;         for (int vt = 0; vt < 4; ++vt) va[(st + 1) & 1][vt] = *(const bf16x8*)(vbase + 32 * vt * VROW + (st + 1) * 32);
;       }
;       float pv[8];
; #pragma unroll
;       for (int i = 0; i < 8; ++i) { pv[i] = ex2(sc[st >> 1][8 * (st & 1) + i] - m); ls[i & 3] += pv[i]; }
;       u32x4 pk; pk.x = pack2(pv[0], pv[1]); pk.y = pack2(pv[2], pv[3]); pk.z = pack2(pv[4], pv[5]); pk.w = pack2(pv[6], pv[7]);
;       const bf16x8 pb = __builtin_bit_cast(bf16x8, pk);
; #pragma unroll
;       for (int vt = 0; vt < 4; ++vt) o[vt] = MFMA32(va[st & 1][vt], pb, o[vt]);
;     }
;     l += (ls[0] + ls[1]) + (ls[2] + ls[3]);
;     __syncthreads();
;     sc[0] = sn[0]; sc[1] = sn[1];
;     { const int tmp = c0; c0 = c1; c1 = c2; c2 = tmp; }
;   }
.Lat_top_0:
	s_min_i32 s60, s6, 0x80
	s_add_i32 s60, s60, 3
	s_waitcnt vmcnt(0)
	ds_write_b128 v165, v[158:161] offset:0
	v_lshl_add_u32 v177, s60, 17, v175
	global_load_dwordx4 v[158:161], v177, s[52:53]
	ds_write_b128 v165, v[154:157] offset:8704
	global_load_dwordx4 v[154:157], v177, s[54:55]
	ds_write_b64 v174, v[146:147] offset:17408
	ds_write_b64 v174, v[148:149] offset:17424
	v_lshl_add_u32 v177, s60, 7, v176
	global_load_dwordx4 v[146:149], v177, s[56:57]
	ds_write_b64 v174, v[150:151] offset:26624
	ds_write_b64 v174, v[152:153] offset:26640
	global_load_dwordx4 v[150:153], v177, s[58:59]
	s_waitcnt lgkmcnt(11)
	v_mfma_f32_32x32x16_bf16 v[82:97], v[208:211], v[130:133], v[66:81]
	ds_read_b128 v[208:211], v206 offset:35936
	v_exp_f32_e32 v246, v114
	v_exp_f32_e32 v247, v115
	v_exp_f32_e32 v248, v116
	v_exp_f32_e32 v249, v117
	v_add_f32_e32 v197, v197, v246
	s_waitcnt lgkmcnt(10)
	v_mfma_f32_32x32x16_bf16 v[82:97], v[212:215], v[134:137], v[82:97]
	v_add_f32_e32 v207, v207, v247
	v_cvt_pk_bf16_f32 v242, v246, v247
	v_exp_f32_e32 v250, v118
	v_add_f32_e32 v197, v197, v248
	v_add_f32_e32 v207, v207, v249
	s_waitcnt lgkmcnt(8)
	v_mfma_f32_32x32x16_bf16 v[82:97], v[216:219], v[138:141], v[82:97]
	v_cvt_pk_bf16_f32 v243, v248, v249
	v_exp_f32_e32 v251, v119
	v_exp_f32_e32 v237, v120
	v_add_f32_e32 v197, v197, v250
	v_exp_f32_e32 v196, v121
	s_waitcnt lgkmcnt(0)
	v_mfma_f32_32x32x16_bf16 v[82:97], v[208:211], v[142:145], v[82:97]
	v_add_f32_e32 v207, v207, v251
	v_cvt_pk_bf16_f32 v244, v250, v251
	v_cvt_pk_bf16_f32 v245, v237, v196
	v_add_f32_e32 v197, v197, v237
	v_add_f32_e32 v207, v207, v196
	v_mfma_f32_32x32x16_bf16 v[34:49], v[220:223], v[242:245], v[34:49]
	ds_read_b128 v[220:223], v163 offset:17440
	v_exp_f32_e32 v246, v122
	v_exp_f32_e32 v247, v123
	v_exp_f32_e32 v248, v124
	v_exp_f32_e32 v249, v125
	v_add_f32_e32 v197, v197, v246
	v_mfma_f32_32x32x16_bf16 v[18:33], v[224:227], v[242:245], v[18:33]
	ds_read_b128 v[224:227], v163 offset:22048
	v_add_f32_e32 v207, v207, v247
	v_cvt_pk_bf16_f32 v170, v246, v247
	v_exp_f32_e32 v250, v126
	v_add_f32_e32 v197, v197, v248
	v_add_f32_e32 v207, v207, v249
	v_mfma_f32_32x32x16_bf16 v[2:17], v[228:231], v[242:245], v[2:17]
	ds_read_b128 v[228:231], v163 offset:26656
	v_cvt_pk_bf16_f32 v171, v248, v249
	v_exp_f32_e32 v251, v127
	v_exp_f32_e32 v237, v128
	v_add_f32_e32 v197, v197, v250
	v_exp_f32_e32 v196, v129
	v_mfma_f32_32x32x16_bf16 v[50:65], v[238:241], v[242:245], v[50:65]
	ds_read_b128 v[238:241], v163 offset:31264
	v_add_f32_e32 v207, v207, v251
	v_cvt_pk_bf16_f32 v172, v250, v251
	v_cvt_pk_bf16_f32 v173, v237, v196
	v_add_f32_e32 v197, v197, v237
	v_add_f32_e32 v207, v207, v196
	s_waitcnt lgkmcnt(3)
	v_mfma_f32_32x32x16_bf16 v[34:49], v[220:223], v[170:173], v[34:49]
	ds_read_b128 v[220:223], v163 offset:17472
	v_exp_f32_e32 v246, v98
	v_exp_f32_e32 v247, v99
	v_exp_f32_e32 v248, v100
	v_exp_f32_e32 v249, v101
	v_add_f32_e32 v197, v197, v246
	s_waitcnt lgkmcnt(3)
	v_mfma_f32_32x32x16_bf16 v[18:33], v[224:227], v[170:173], v[18:33]
	ds_read_b128 v[224:227], v163 offset:22080
	v_add_f32_e32 v207, v207, v247
	v_cvt_pk_bf16_f32 v242, v246, v247
	v_exp_f32_e32 v250, v102
	v_add_f32_e32 v197, v197, v248
	v_add_f32_e32 v207, v207, v249
	s_waitcnt lgkmcnt(3)
	v_mfma_f32_32x32x16_bf16 v[2:17], v[228:231], v[170:173], v[2:17]
	ds_read_b128 v[228:231], v163 offset:26688
	v_cvt_pk_bf16_f32 v243, v248, v249
	v_exp_f32_e32 v251, v103
	v_exp_f32_e32 v237, v104
	v_add_f32_e32 v197, v197, v250
	v_exp_f32_e32 v196, v105
	s_waitcnt lgkmcnt(3)
	v_mfma_f32_32x32x16_bf16 v[50:65], v[238:241], v[170:173], v[50:65]
	ds_read_b128 v[238:241], v163 offset:31296
	v_add_f32_e32 v207, v207, v251
	v_cvt_pk_bf16_f32 v244, v250, v251
	v_cvt_pk_bf16_f32 v245, v237, v196
	v_add_f32_e32 v197, v197, v237
	v_add_f32_e32 v207, v207, v196
	s_waitcnt lgkmcnt(3)
	v_mfma_f32_32x32x16_bf16 v[34:49], v[220:223], v[242:245], v[34:49]
	ds_read_b128 v[220:223], v163 offset:17504
	ds_read_b128 v[212:215], v206 offset:44544
	v_exp_f32_e32 v246, v106
	v_exp_f32_e32 v247, v107
	v_exp_f32_e32 v248, v108
	v_exp_f32_e32 v249, v109
	v_add_f32_e32 v197, v197, v246
	s_waitcnt lgkmcnt(4)
	v_mfma_f32_32x32x16_bf16 v[18:33], v[224:227], v[242:245], v[18:33]
	ds_read_b128 v[224:227], v163 offset:22112
	ds_read_b128 v[216:219], v206 offset:44576
	v_add_f32_e32 v207, v207, v247
	v_cvt_pk_bf16_f32 v170, v246, v247
	v_exp_f32_e32 v250, v110
	v_add_f32_e32 v197, v197, v248
	v_add_f32_e32 v207, v207, v249
	s_waitcnt lgkmcnt(5)
	v_mfma_f32_32x32x16_bf16 v[2:17], v[228:231], v[242:245], v[2:17]
	ds_read_b128 v[228:231], v163 offset:26720
	ds_read_b128 v[208:211], v206 offset:44608
	v_cvt_pk_bf16_f32 v171, v248, v249
	v_exp_f32_e32 v251, v111
	v_exp_f32_e32 v237, v112
	v_add_f32_e32 v197, v197, v250
	v_exp_f32_e32 v196, v113
	s_waitcnt lgkmcnt(6)
	v_mfma_f32_32x32x16_bf16 v[50:65], v[238:241], v[242:245], v[50:65]
	ds_read_b128 v[238:241], v163 offset:31328
	v_add_f32_e32 v207, v207, v251
	v_cvt_pk_bf16_f32 v172, v250, v251
	v_cvt_pk_bf16_f32 v173, v237, v196
	v_add_f32_e32 v197, v197, v237
	v_add_f32_e32 v207, v207, v196
	s_waitcnt lgkmcnt(5)
	v_mfma_f32_32x32x16_bf16 v[114:129], v[212:215], v[130:133], v[66:81]
	ds_read_b128 v[212:215], v206 offset:44640
	v_max3_f32 v178, v82, v83, v84
	s_waitcnt lgkmcnt(4)
	v_mfma_f32_32x32x16_bf16 v[114:129], v[216:219], v[134:137], v[114:129]
	v_max3_f32 v179, v85, v86, v87
	s_waitcnt lgkmcnt(2)
	v_mfma_f32_32x32x16_bf16 v[114:129], v[208:211], v[138:141], v[114:129]
	v_max3_f32 v178, v178, v88, v89
	s_waitcnt lgkmcnt(0)
	v_mfma_f32_32x32x16_bf16 v[114:129], v[212:215], v[142:145], v[114:129]
	v_max3_f32 v179, v179, v90, v91
	s_waitcnt lgkmcnt(0)
	s_barrier
	v_mfma_f32_32x32x16_bf16 v[34:49], v[220:223], v[170:173], v[34:49]
	ds_read_b128 v[220:223], v164 offset:0
	ds_read_b128 v[208:211], v162 offset:0
	v_max3_f32 v178, v178, v92, v93
	v_max3_f32 v179, v179, v94, v95
	v_mfma_f32_32x32x16_bf16 v[18:33], v[224:227], v[170:173], v[18:33]
	ds_read_b128 v[224:227], v164 offset:4608
	ds_read_b128 v[212:215], v162 offset:32
	v_max3_f32 v178, v178, v96, v97
	v_mfma_f32_32x32x16_bf16 v[2:17], v[228:231], v[170:173], v[2:17]
	ds_read_b128 v[228:231], v164 offset:9216
	ds_read_b128 v[216:219], v162 offset:64
	v_max3_f32 v179, v179, v114, v115
	v_max3_f32 v178, v178, v116, v117
	v_max3_f32 v179, v179, v118, v119
	v_max3_f32 v178, v178, v120, v121
	v_mfma_f32_32x32x16_bf16 v[50:65], v[238:241], v[170:173], v[50:65]
	ds_read_b128 v[238:241], v164 offset:13824
	v_max3_f32 v179, v179, v122, v123
	v_max3_f32 v178, v178, v124, v125
	v_max3_f32 v179, v179, v126, v127
	v_max3_f32 v178, v178, v128, v129
	v_max_f32_e32 v178, v178, v179
	v_mov_b32_e32 v179, v178
	s_nop 1
	v_permlane32_swap_b32_e32 v178, v179
	v_max_f32_e32 v178, v178, v179
	v_cmp_lt_f32_e32 vcc, 0x41000000, v178
	s_cbranch_vccnz .Lat_rare_0

; #define MFMA32(a, b, c) __builtin_amdgcn_mfma_f32_32x32x16_bf16((a), (b), (c), 0, 0, 0)
; DI float ex2(float x) { return __builtin_amdgcn_exp2f(x); }
; #define A_LOAD(KB) { _Pragma("unroll") for (int i = 0; i < 2; ++i) { rk[i] = *(const u32x4*)(kp + (size_t)((KB) * 64 + 32 * i) * 1024); rv[i] = *(const u32x4*)(vp + (size_t)(64 * i) * TOK + (KB) * 64); } }
; DI void attn_block(const Params& p, int layer, int hd, int q0, int nkeys, char* smem) {
;     ...
;   for (int kb = 0; kb < nkb; ++kb) {
;     const char* Vs = smem + c0 * ST + KT;
;     A_STORE(c2);
;     A_LOAD((kb + 3 < lastkb) ? kb + 3 : lastkb);
;     if (kb + 1 < nkb) A_SCORES(sn, c1);
;     float mx = fmaxf(sc[0][0], sc[1][0]);
; #pragma unroll
;     for (int i = 1; i < 16; ++i) mx = fmaxf(mx, fmaxf(sc[0][i], sc[1][i]));
;     {
;       const auto pr_ = __builtin_amdgcn_permlane32_swap(__float_as_uint(mx), __float_as_uint(mx), false, false);
;       mx = fmaxf(__uint_as_float(pr_[0]), __uint_as_float(pr_[1]));
;     }
;     if (__any(mx > m + 8.f)) {
;       const float mn = (mx > m + 8.f) ? mx : m;
;       const float alpha = ex2(m - mn);
;       l *= alpha;
; #pragma unroll
;       for (int vt = 0; vt < 4; ++vt)
; #pragma unroll
;         for (int i = 0; i < 16; ++i) o[vt][i] *= alpha;
;       m = mn;
;     }
;     bf16x8 va[2][4];
;     const char* vbase = Vs + r * VROW + 16 * h;
; #pragma unroll
;     for (int vt = 0; vt < 4; ++vt) va[0][vt] = *(const bf16x8*)(vbase + 32 * vt * VROW);
;     float ls[4] = {0.f, 0.f, 0.f, 0.f};
; #pragma unroll
;     for (int st = 0; st < 4; ++st) {
;       if (st < 3) {
; #pragma unroll
;         for (int vt = 0; vt < 4; ++vt) va[(st + 1) & 1][vt] = *(const bf16x8*)(vbase + 32 * vt * VROW + (st + 1) * 32);
;       }
;       float pv[8];
; #pragma unroll
;       for (int i = 0; i < 8; ++i) { pv[i] = ex2(sc[st >> 1][8 * (st & 1) + i] - m); ls[i & 3] += pv[i]; }
;       u32x4 pk; pk.x = pack2(pv[0], pv[1]); pk.y = pack2(pv[2], pv[3]); pk.z = pack2(pv[4], pv[5]); pk.w = pack2(pv[6], pv[7]);
;       const bf16x8 pb = __builtin_bit_cast(bf16x8, pk);
; #pragma unroll
;       for (int vt = 0; vt < 4; ++vt) o[vt] = MFMA32(va[st & 1][vt], pb, o[vt]);
;     }
;     l += (ls[0] + ls[1]) + (ls[2] + ls[3]);
;     __syncthreads();
;     sc[0] = sn[0]; sc[1] = sn[1];
;     { const int tmp = c0; c0 = c1; c1 = c2; c2 = tmp; }
;   }
.Lat_top_1:
	s_min_i32 s60, s6, 0x80
	s_add_i32 s60, s60, 3
	s_waitcnt vmcnt(0)
	ds_write_b128 v194, v[158:161] offset:16
	v_lshl_add_u32 v177, s60, 17, v175
	global_load_dwordx4 v[158:161], v177, s[52:53]
	ds_write_b128 v194, v[154:157] offset:8720
	global_load_dwordx4 v[154:157], v177, s[54:55]
	ds_write_b64 v205, v[146:147] offset:17424
	ds_write_b64 v205, v[148:149] offset:17440
	v_lshl_add_u32 v177, s60, 7, v176
	global_load_dwordx4 v[146:149], v177, s[56:57]
	ds_write_b64 v205, v[150:151] offset:26640
	ds_write_b64 v205, v[152:153] offset:26656
	global_load_dwordx4 v[150:153], v177, s[58:59]
	s_waitcnt lgkmcnt(11)
	v_mfma_f32_32x32x16_bf16 v[98:113], v[208:211], v[130:133], v[66:81]
	ds_read_b128 v[208:211], v162 offset:96
	v_exp_f32_e32 v246, v82
	v_exp_f32_e32 v247, v83
	v_exp_f32_e32 v248, v84
	v_exp_f32_e32 v249, v85
	v_add_f32_e32 v197, v197, v246
	s_waitcnt lgkmcnt(10)
	v_mfma_f32_32x32x16_bf16 v[98:113], v[212:215], v[134:137], v[98:113]
	v_add_f32_e32 v207, v207, v247
	v_cvt_pk_bf16_f32 v242, v246, v247
	v_exp_f32_e32 v250, v86
	v_add_f32_e32 v197, v197, v248
	v_add_f32_e32 v207, v207, v249
	s_waitcnt lgkmcnt(8)
	v_mfma_f32_32x32x16_bf16 v[98:113], v[216:219], v[138:141], v[98:113]
	v_cvt_pk_bf16_f32 v243, v248, v249
	v_exp_f32_e32 v251, v87
	v_exp_f32_e32 v237, v88
	v_add_f32_e32 v197, v197, v250
	v_exp_f32_e32 v196, v89
	s_waitcnt lgkmcnt(0)
	v_mfma_f32_32x32x16_bf16 v[98:113], v[208:211], v[142:145], v[98:113]
	v_add_f32_e32 v207, v207, v251
	v_cvt_pk_bf16_f32 v244, v250, v251
	v_cvt_pk_bf16_f32 v245, v237, v196
	v_add_f32_e32 v197, v197, v237
	v_add_f32_e32 v207, v207, v196
	v_mfma_f32_32x32x16_bf16 v[34:49], v[220:223], v[242:245], v[34:49]
	ds_read_b128 v[220:223], v164 offset:32
	v_exp_f32_e32 v246, v90
	v_exp_f32_e32 v247, v91
	v_exp_f32_e32 v248, v92
	v_exp_f32_e32 v249, v93
	v_add_f32_e32 v197, v197, v246
	v_mfma_f32_32x32x16_bf16 v[18:33], v[224:227], v[242:245], v[18:33]
	ds_read_b128 v[224:227], v164 offset:4640
	v_add_f32_e32 v207, v207, v247
	v_cvt_pk_bf16_f32 v170, v246, v247
	v_exp_f32_e32 v250, v94
	v_add_f32_e32 v197, v197, v248
	v_add_f32_e32 v207, v207, v249
	v_mfma_f32_32x32x16_bf16 v[2:17], v[228:231], v[242:245], v[2:17]
	ds_read_b128 v[228:231], v164 offset:9248
	v_cvt_pk_bf16_f32 v171, v248, v249
	v_exp_f32_e32 v251, v95
	v_exp_f32_e32 v237, v96
	v_add_f32_e32 v197, v197, v250
	v_exp_f32_e32 v196, v97
	v_mfma_f32_32x32x16_bf16 v[50:65], v[238:241], v[242:245], v[50:65]
	ds_read_b128 v[238:241], v164 offset:13856
	v_add_f32_e32 v207, v207, v251
	v_cvt_pk_bf16_f32 v172, v250, v251
	v_cvt_pk_bf16_f32 v173, v237, v196
	v_add_f32_e32 v197, v197, v237
	v_add_f32_e32 v207, v207, v196
	s_waitcnt lgkmcnt(3)
	v_mfma_f32_32x32x16_bf16 v[34:49], v[220:223], v[170:173], v[34:49]
	ds_read_b128 v[220:223], v164 offset:64
	v_exp_f32_e32 v246, v114
	v_exp_f32_e32 v247, v115
	v_exp_f32_e32 v248, v116
	v_exp_f32_e32 v249, v117
	v_add_f32_e32 v197, v197, v246
	s_waitcnt lgkmcnt(3)
	v_mfma_f32_32x32x16_bf16 v[18:33], v[224:227], v[170:173], v[18:33]
	ds_read_b128 v[224:227], v164 offset:4672
	v_add_f32_e32 v207, v207, v247
	v_cvt_pk_bf16_f32 v242, v246, v247
	v_exp_f32_e32 v250, v118
	v_add_f32_e32 v197, v197, v248
	v_add_f32_e32 v207, v207, v249
	s_waitcnt lgkmcnt(3)
	v_mfma_f32_32x32x16_bf16 v[2:17], v[228:231], v[170:173], v[2:17]
	ds_read_b128 v[228:231], v164 offset:9280
	v_cvt_pk_bf16_f32 v243, v248, v249
	v_exp_f32_e32 v251, v119
	v_exp_f32_e32 v237, v120
	v_add_f32_e32 v197, v197, v250
	v_exp_f32_e32 v196, v121
	s_waitcnt lgkmcnt(3)
	v_mfma_f32_32x32x16_bf16 v[50:65], v[238:241], v[170:173], v[50:65]
	ds_read_b128 v[238:241], v164 offset:13888
	v_add_f32_e32 v207, v207, v251
	v_cvt_pk_bf16_f32 v244, v250, v251
	v_cvt_pk_bf16_f32 v245, v237, v196
	v_add_f32_e32 v197, v197, v237
	v_add_f32_e32 v207, v207, v196
	s_waitcnt lgkmcnt(3)
	v_mfma_f32_32x32x16_bf16 v[34:49], v[220:223], v[242:245], v[34:49]
	ds_read_b128 v[220:223], v164 offset:96
	ds_read_b128 v[212:215], v162 offset:8704
	v_exp_f32_e32 v246, v122
	v_exp_f32_e32 v247, v123
	v_exp_f32_e32 v248, v124
	v_exp_f32_e32 v249, v125
	v_add_f32_e32 v197, v197, v246
	s_waitcnt lgkmcnt(4)
	v_mfma_f32_32x32x16_bf16 v[18:33], v[224:227], v[242:245], v[18:33]
	ds_read_b128 v[224:227], v164 offset:4704
	ds_read_b128 v[216:219], v162 offset:8736
	v_add_f32_e32 v207, v207, v247
	v_cvt_pk_bf16_f32 v170, v246, v247
	v_exp_f32_e32 v250, v126
	v_add_f32_e32 v197, v197, v248
	v_add_f32_e32 v207, v207, v249
	s_waitcnt lgkmcnt(5)
	v_mfma_f32_32x32x16_bf16 v[2:17], v[228:231], v[242:245], v[2:17]
	ds_read_b128 v[228:231], v164 offset:9312
	ds_read_b128 v[208:211], v162 offset:8768
	v_cvt_pk_bf16_f32 v171, v248, v249
	v_exp_f32_e32 v251, v127
	v_exp_f32_e32 v237, v128
	v_add_f32_e32 v197, v197, v250
	v_exp_f32_e32 v196, v129
	s_waitcnt lgkmcnt(6)
	v_mfma_f32_32x32x16_bf16 v[50:65], v[238:241], v[242:245], v[50:65]
	ds_read_b128 v[238:241], v164 offset:13920
	v_add_f32_e32 v207, v207, v251
	v_cvt_pk_bf16_f32 v172, v250, v251
	v_cvt_pk_bf16_f32 v173, v237, v196
	v_add_f32_e32 v197, v197, v237
	v_add_f32_e32 v207, v207, v196
	s_waitcnt lgkmcnt(5)
	v_mfma_f32_32x32x16_bf16 v[82:97], v[212:215], v[130:133], v[66:81]
	ds_read_b128 v[212:215], v162 offset:8800
	v_max3_f32 v178, v98, v99, v100
	s_waitcnt lgkmcnt(4)
	v_mfma_f32_32x32x16_bf16 v[82:97], v[216:219], v[134:137], v[82:97]
	v_max3_f32 v179, v101, v102, v103
	s_waitcnt lgkmcnt(2)
	v_mfma_f32_32x32x16_bf16 v[82:97], v[208:211], v[138:141], v[82:97]
	v_max3_f32 v178, v178, v104, v105
	s_waitcnt lgkmcnt(0)
	v_mfma_f32_32x32x16_bf16 v[82:97], v[212:215], v[142:145], v[82:97]
	v_max3_f32 v179, v179, v106, v107
	s_waitcnt lgkmcnt(0)
	s_barrier
	v_mfma_f32_32x32x16_bf16 v[34:49], v[220:223], v[170:173], v[34:49]
	ds_read_b128 v[220:223], v164 offset:35840
	ds_read_b128 v[208:211], v206 offset:0
	v_max3_f32 v178, v178, v108, v109
	v_max3_f32 v179, v179, v110, v111
	v_mfma_f32_32x32x16_bf16 v[18:33], v[224:227], v[170:173], v[18:33]
	ds_read_b128 v[224:227], v164 offset:40448
	ds_read_b128 v[212:215], v206 offset:32
	v_max3_f32 v178, v178, v112, v113
	v_mfma_f32_32x32x16_bf16 v[2:17], v[228:231], v[170:173], v[2:17]
	ds_read_b128 v[228:231], v164 offset:45056
	ds_read_b128 v[216:219], v206 offset:64
	v_max3_f32 v179, v179, v82, v83
	v_max3_f32 v178, v178, v84, v85
	v_max3_f32 v179, v179, v86, v87
	v_max3_f32 v178, v178, v88, v89
	v_mfma_f32_32x32x16_bf16 v[50:65], v[238:241], v[170:173], v[50:65]
	ds_read_b128 v[238:241], v164 offset:49664
	v_max3_f32 v179, v179, v90, v91
	v_max3_f32 v178, v178, v92, v93
	v_max3_f32 v179, v179, v94, v95
	v_max3_f32 v178, v178, v96, v97
	v_max_f32_e32 v178, v178, v179
	v_mov_b32_e32 v179, v178
	s_nop 1
	v_permlane32_swap_b32_e32 v178, v179
	v_max_f32_e32 v178, v178, v179
	v_cmp_lt_f32_e32 vcc, 0x41000000, v178
	s_cbranch_vccnz .Lat_rare_1

; #define MFMA32(a, b, c) __builtin_amdgcn_mfma_f32_32x32x16_bf16((a), (b), (c), 0, 0, 0)
; DI float ex2(float x) { return __builtin_amdgcn_exp2f(x); }
; #define A_LOAD(KB) { _Pragma("unroll") for (int i = 0; i < 2; ++i) { rk[i] = *(const u32x4*)(kp + (size_t)((KB) * 64 + 32 * i) * 1024); rv[i] = *(const u32x4*)(vp + (size_t)(64 * i) * TOK + (KB) * 64); } }
; DI void attn_block(const Params& p, int layer, int hd, int q0, int nkeys, char* smem) {
;     ...
;   for (int kb = 0; kb < nkb; ++kb) {
;     const char* Vs = smem + c0 * ST + KT;
;     A_STORE(c2);
;     A_LOAD((kb + 3 < lastkb) ? kb + 3 : lastkb);
;     if (kb + 1 < nkb) A_SCORES(sn, c1);
;     float mx = fmaxf(sc[0][0], sc[1][0]);
; #pragma unroll
;     for (int i = 1; i < 16; ++i) mx = fmaxf(mx, fmaxf(sc[0][i], sc[1][i]));
;     {
;       const auto pr_ = __builtin_amdgcn_permlane32_swap(__float_as_uint(mx), __float_as_uint(mx), false, false);
;       mx = fmaxf(__uint_as_float(pr_[0]), __uint_as_float(pr_[1]));
;     }
;     if (__any(mx > m + 8.f)) {
;       const float mn = (mx > m + 8.f) ? mx : m;
;       const float alpha = ex2(m - mn);
;       l *= alpha;
; #pragma unroll
;       for (int vt = 0; vt < 4; ++vt)
; #pragma unroll
;         for (int i = 0; i < 16; ++i) o[vt][i] *= alpha;
;       m = mn;
;     }
;     bf16x8 va[2][4];
;     const char* vbase = Vs + r * VROW + 16 * h;
; #pragma unroll
;     for (int vt = 0; vt < 4; ++vt) va[0][vt] = *(const bf16x8*)(vbase + 32 * vt * VROW);
;     float ls[4] = {0.f, 0.f, 0.f, 0.f};
; #pragma unroll
;     for (int st = 0; st < 4; ++st) {
;       if (st < 3) {
; #pragma unroll
;         for (int vt = 0; vt < 4; ++vt) va[(st + 1) & 1][vt] = *(const bf16x8*)(vbase + 32 * vt * VROW + (st + 1) * 32);
;       }
;       float pv[8];
; #pragma unroll
;       for (int i = 0; i < 8; ++i) { pv[i] = ex2(sc[st >> 1][8 * (st & 1) + i] - m); ls[i & 3] += pv[i]; }
;       u32x4 pk; pk.x = pack2(pv[0], pv[1]); pk.y = pack2(pv[2], pv[3]); pk.z = pack2(pv[4], pv[5]); pk.w = pack2(pv[6], pv[7]);
;       const bf16x8 pb = __builtin_bit_cast(bf16x8, pk);
; #pragma unroll
;       for (int vt = 0; vt < 4; ++vt) o[vt] = MFMA32(va[st & 1][vt], pb, o[vt]);
;     }
;     l += (ls[0] + ls[1]) + (ls[2] + ls[3]);
;     __syncthreads();
;     sc[0] = sn[0]; sc[1] = sn[1];
;     { const int tmp = c0; c0 = c1; c1 = c2; c2 = tmp; }
;   }
.Lat_top_2:
	s_min_i32 s60, s6, 0x80
	s_add_i32 s60, s60, 3
	s_waitcnt vmcnt(0)
	ds_write_b128 v194, v[158:161] offset:35856
	v_lshl_add_u32 v177, s60, 17, v175
	global_load_dwordx4 v[158:161], v177, s[52:53]
	ds_write_b128 v194, v[154:157] offset:44560
	global_load_dwordx4 v[154:157], v177, s[54:55]
	ds_write_b64 v205, v[146:147] offset:53264
	ds_write_b64 v205, v[148:149] offset:53280
	v_lshl_add_u32 v177, s60, 7, v176
	global_load_dwordx4 v[146:149], v177, s[56:57]
	ds_write_b64 v205, v[150:151] offset:62480
	ds_write_b64 v205, v[152:153] offset:62496
	global_load_dwordx4 v[150:153], v177, s[58:59]
	s_waitcnt lgkmcnt(11)
	v_mfma_f32_32x32x16_bf16 v[114:129], v[208:211], v[130:133], v[66:81]
	ds_read_b128 v[208:211], v206 offset:96
	v_exp_f32_e32 v246, v98
	v_exp_f32_e32 v247, v99
	v_exp_f32_e32 v248, v100
	v_exp_f32_e32 v249, v101
	v_add_f32_e32 v197, v197, v246
	s_waitcnt lgkmcnt(10)
	v_mfma_f32_32x32x16_bf16 v[114:129], v[212:215], v[134:137], v[114:129]
	v_add_f32_e32 v207, v207, v247
	v_cvt_pk_bf16_f32 v242, v246, v247
	v_exp_f32_e32 v250, v102
	v_add_f32_e32 v197, v197, v248
	v_add_f32_e32 v207, v207, v249
	s_waitcnt lgkmcnt(8)
	v_mfma_f32_32x32x16_bf16 v[114:129], v[216:219], v[138:141], v[114:129]
	v_cvt_pk_bf16_f32 v243, v248, v249
	v_exp_f32_e32 v251, v103
	v_exp_f32_e32 v237, v104
	v_add_f32_e32 v197, v197, v250
	v_exp_f32_e32 v196, v105
	s_waitcnt lgkmcnt(0)
	v_mfma_f32_32x32x16_bf16 v[114:129], v[208:211], v[142:145], v[114:129]
	v_add_f32_e32 v207, v207, v251
	v_cvt_pk_bf16_f32 v244, v250, v251
	v_cvt_pk_bf16_f32 v245, v237, v196
	v_add_f32_e32 v197, v197, v237
	v_add_f32_e32 v207, v207, v196
	v_mfma_f32_32x32x16_bf16 v[34:49], v[220:223], v[242:245], v[34:49]
	ds_read_b128 v[220:223], v164 offset:35872
	v_exp_f32_e32 v246, v106
	v_exp_f32_e32 v247, v107
	v_exp_f32_e32 v248, v108
	v_exp_f32_e32 v249, v109
	v_add_f32_e32 v197, v197, v246
	v_mfma_f32_32x32x16_bf16 v[18:33], v[224:227], v[242:245], v[18:33]
	ds_read_b128 v[224:227], v164 offset:40480
	v_add_f32_e32 v207, v207, v247
	v_cvt_pk_bf16_f32 v170, v246, v247
	v_exp_f32_e32 v250, v110
	v_add_f32_e32 v197, v197, v248
	v_add_f32_e32 v207, v207, v249
	v_mfma_f32_32x32x16_bf16 v[2:17], v[228:231], v[242:245], v[2:17]
	ds_read_b128 v[228:231], v164 offset:45088
	v_cvt_pk_bf16_f32 v171, v248, v249
	v_exp_f32_e32 v251, v111
	v_exp_f32_e32 v237, v112
	v_add_f32_e32 v197, v197, v250
	v_exp_f32_e32 v196, v113
	v_mfma_f32_32x32x16_bf16 v[50:65], v[238:241], v[242:245], v[50:65]
	ds_read_b128 v[238:241], v164 offset:49696
	v_add_f32_e32 v207, v207, v251
	v_cvt_pk_bf16_f32 v172, v250, v251
	v_cvt_pk_bf16_f32 v173, v237, v196
	v_add_f32_e32 v197, v197, v237
	v_add_f32_e32 v207, v207, v196
	s_waitcnt lgkmcnt(3)
	v_mfma_f32_32x32x16_bf16 v[34:49], v[220:223], v[170:173], v[34:49]
	ds_read_b128 v[220:223], v164 offset:35904
	v_exp_f32_e32 v246, v82
	v_exp_f32_e32 v247, v83
	v_exp_f32_e32 v248, v84
	v_exp_f32_e32 v249, v85
	v_add_f32_e32 v197, v197, v246
	s_waitcnt lgkmcnt(3)
	v_mfma_f32_32x32x16_bf16 v[18:33], v[224:227], v[170:173], v[18:33]
	ds_read_b128 v[224:227], v164 offset:40512
	v_add_f32_e32 v207, v207, v247
	v_cvt_pk_bf16_f32 v242, v246, v247
	v_exp_f32_e32 v250, v86
	v_add_f32_e32 v197, v197, v248
	v_add_f32_e32 v207, v207, v249
	s_waitcnt lgkmcnt(3)
	v_mfma_f32_32x32x16_bf16 v[2:17], v[228:231], v[170:173], v[2:17]
	ds_read_b128 v[228:231], v164 offset:45120
	v_cvt_pk_bf16_f32 v243, v248, v249
	v_exp_f32_e32 v251, v87
	v_exp_f32_e32 v237, v88
	v_add_f32_e32 v197, v197, v250
	v_exp_f32_e32 v196, v89
	s_waitcnt lgkmcnt(3)
	v_mfma_f32_32x32x16_bf16 v[50:65], v[238:241], v[170:173], v[50:65]
	ds_read_b128 v[238:241], v164 offset:49728
	v_add_f32_e32 v207, v207, v251
	v_cvt_pk_bf16_f32 v244, v250, v251
	v_cvt_pk_bf16_f32 v245, v237, v196
	v_add_f32_e32 v197, v197, v237
	v_add_f32_e32 v207, v207, v196
	s_waitcnt lgkmcnt(3)
	v_mfma_f32_32x32x16_bf16 v[34:49], v[220:223], v[242:245], v[34:49]
	ds_read_b128 v[220:223], v164 offset:35936
	ds_read_b128 v[212:215], v206 offset:8704
	v_exp_f32_e32 v246, v90
	v_exp_f32_e32 v247, v91
	v_exp_f32_e32 v248, v92
	v_exp_f32_e32 v249, v93
	v_add_f32_e32 v197, v197, v246
	s_waitcnt lgkmcnt(4)
	v_mfma_f32_32x32x16_bf16 v[18:33], v[224:227], v[242:245], v[18:33]
	ds_read_b128 v[224:227], v164 offset:40544
	ds_read_b128 v[216:219], v206 offset:8736
	v_add_f32_e32 v207, v207, v247
	v_cvt_pk_bf16_f32 v170, v246, v247
	v_exp_f32_e32 v250, v94
	v_add_f32_e32 v197, v197, v248
	v_add_f32_e32 v207, v207, v249
	s_waitcnt lgkmcnt(5)
	v_mfma_f32_32x32x16_bf16 v[2:17], v[228:231], v[242:245], v[2:17]
	ds_read_b128 v[228:231], v164 offset:45152
	ds_read_b128 v[208:211], v206 offset:8768
	v_cvt_pk_bf16_f32 v171, v248, v249
	v_exp_f32_e32 v251, v95
	v_exp_f32_e32 v237, v96
	v_add_f32_e32 v197, v197, v250
	v_exp_f32_e32 v196, v97
	s_waitcnt lgkmcnt(6)
	v_mfma_f32_32x32x16_bf16 v[50:65], v[238:241], v[242:245], v[50:65]
	ds_read_b128 v[238:241], v164 offset:49760
	v_add_f32_e32 v207, v207, v251
	v_cvt_pk_bf16_f32 v172, v250, v251
	v_cvt_pk_bf16_f32 v173, v237, v196
	v_add_f32_e32 v197, v197, v237
	v_add_f32_e32 v207, v207, v196
	s_waitcnt lgkmcnt(5)
	v_mfma_f32_32x32x16_bf16 v[98:113], v[212:215], v[130:133], v[66:81]
	ds_read_b128 v[212:215], v206 offset:8800
	v_max3_f32 v178, v114, v115, v116
	s_waitcnt lgkmcnt(4)
	v_mfma_f32_32x32x16_bf16 v[98:113], v[216:219], v[134:137], v[98:113]
	v_max3_f32 v179, v117, v118, v119
	s_waitcnt lgkmcnt(2)
	v_mfma_f32_32x32x16_bf16 v[98:113], v[208:211], v[138:141], v[98:113]
	v_max3_f32 v178, v178, v120, v121
	s_waitcnt lgkmcnt(0)
	v_mfma_f32_32x32x16_bf16 v[98:113], v[212:215], v[142:145], v[98:113]
	v_max3_f32 v179, v179, v122, v123
	s_waitcnt lgkmcnt(0)
	s_barrier
	v_mfma_f32_32x32x16_bf16 v[34:49], v[220:223], v[170:173], v[34:49]
	ds_read_b128 v[220:223], v163 offset:17408
	ds_read_b128 v[208:211], v206 offset:35840
	v_max3_f32 v178, v178, v124, v125
	v_max3_f32 v179, v179, v126, v127
	v_mfma_f32_32x32x16_bf16 v[18:33], v[224:227], v[170:173], v[18:33]
	ds_read_b128 v[224:227], v163 offset:22016
	ds_read_b128 v[212:215], v206 offset:35872
	v_max3_f32 v178, v178, v128, v129
	v_mfma_f32_32x32x16_bf16 v[2:17], v[228:231], v[170:173], v[2:17]
	ds_read_b128 v[228:231], v163 offset:26624
	ds_read_b128 v[216:219], v206 offset:35904
	v_max3_f32 v179, v179, v98, v99
	v_max3_f32 v178, v178, v100, v101
	v_max3_f32 v179, v179, v102, v103
	v_max3_f32 v178, v178, v104, v105
	v_mfma_f32_32x32x16_bf16 v[50:65], v[238:241], v[170:173], v[50:65]
	ds_read_b128 v[238:241], v163 offset:31232
	v_max3_f32 v179, v179, v106, v107
	v_max3_f32 v178, v178, v108, v109
	v_max3_f32 v179, v179, v110, v111
	v_max3_f32 v178, v178, v112, v113
	v_max_f32_e32 v178, v178, v179
	v_mov_b32_e32 v179, v178
	s_nop 1
	v_permlane32_swap_b32_e32 v178, v179
	v_max_f32_e32 v178, v178, v179
	v_cmp_lt_f32_e32 vcc, 0x41000000, v178
	s_cbranch_vccnz .Lat_rare_2

; DI float ex2(float x) { return __builtin_amdgcn_exp2f(x); }
; DI void attn_block(const Params& p, int layer, int hd, int q0, int nkeys, char* smem) {
;     ...
;     if (__any(mx > m + 8.f)) {
;       const float mn = (mx > m + 8.f) ? mx : m;
;       const float alpha = ex2(m - mn);
;       l *= alpha;
; #pragma unroll
;       for (int vt = 0; vt < 4; ++vt)
; #pragma unroll
;         for (int i = 0; i < 16; ++i) o[vt][i] *= alpha;
;       m = mn;
;     }
.Lat_rare_0:
	s_nop 1
	v_cndmask_b32_e32 v179, 0, v178, vcc
	v_sub_f32_e32 v66, v66, v179
	v_exp_f32_e64 v248, -v179
	v_sub_f32_e32 v82, v82, v179
	v_sub_f32_e32 v83, v83, v179
	v_sub_f32_e32 v84, v84, v179
	v_sub_f32_e32 v85, v85, v179
	v_sub_f32_e32 v86, v86, v179
	v_sub_f32_e32 v87, v87, v179
	v_sub_f32_e32 v88, v88, v179
	v_sub_f32_e32 v89, v89, v179
	v_sub_f32_e32 v90, v90, v179
	v_sub_f32_e32 v91, v91, v179
	v_sub_f32_e32 v92, v92, v179
	v_sub_f32_e32 v93, v93, v179
	v_sub_f32_e32 v94, v94, v179
	v_sub_f32_e32 v95, v95, v179
	v_sub_f32_e32 v96, v96, v179
	v_sub_f32_e32 v97, v97, v179
	v_sub_f32_e32 v114, v114, v179
	v_sub_f32_e32 v115, v115, v179
	v_sub_f32_e32 v116, v116, v179
	v_sub_f32_e32 v117, v117, v179
	v_sub_f32_e32 v118, v118, v179
	v_sub_f32_e32 v119, v119, v179
	v_sub_f32_e32 v120, v120, v179
	v_sub_f32_e32 v121, v121, v179
	v_sub_f32_e32 v122, v122, v179
	v_sub_f32_e32 v123, v123, v179
	v_sub_f32_e32 v124, v124, v179
	v_sub_f32_e32 v125, v125, v179
	v_sub_f32_e32 v126, v126, v179
	v_sub_f32_e32 v127, v127, v179
	v_sub_f32_e32 v128, v128, v179
	v_sub_f32_e32 v129, v129, v179
	v_mov_b32_e32 v67, v66
	v_mov_b32_e32 v68, v66
	v_mov_b32_e32 v69, v66
	v_mov_b32_e32 v70, v66
	v_mov_b32_e32 v71, v66
	v_mov_b32_e32 v72, v66
	v_mov_b32_e32 v73, v66
	v_mov_b32_e32 v74, v66
	v_mov_b32_e32 v75, v66
	v_mov_b32_e32 v76, v66
	v_mov_b32_e32 v77, v66
	v_mov_b32_e32 v78, v66
	v_mov_b32_e32 v79, v66
	v_mov_b32_e32 v80, v66
	v_mov_b32_e32 v81, v66
	v_mul_f32_e32 v197, v197, v248
	v_mul_f32_e32 v207, v207, v248
	v_mul_f32_e32 v34, v34, v248
	v_mul_f32_e32 v35, v35, v248
	v_mul_f32_e32 v36, v36, v248
	v_mul_f32_e32 v37, v37, v248
	v_mul_f32_e32 v38, v38, v248
	v_mul_f32_e32 v39, v39, v248
	v_mul_f32_e32 v40, v40, v248
	v_mul_f32_e32 v41, v41, v248
	v_mul_f32_e32 v42, v42, v248
	v_mul_f32_e32 v43, v43, v248
	v_mul_f32_e32 v44, v44, v248
	v_mul_f32_e32 v45, v45, v248
	v_mul_f32_e32 v46, v46, v248
	v_mul_f32_e32 v47, v47, v248
	v_mul_f32_e32 v48, v48, v248
	v_mul_f32_e32 v49, v49, v248
	v_mul_f32_e32 v18, v18, v248
	v_mul_f32_e32 v19, v19, v248
	v_mul_f32_e32 v20, v20, v248
	v_mul_f32_e32 v21, v21, v248
	v_mul_f32_e32 v22, v22, v248
	v_mul_f32_e32 v23, v23, v248
	v_mul_f32_e32 v24, v24, v248
	v_mul_f32_e32 v25, v25, v248
	v_mul_f32_e32 v26, v26, v248
	v_mul_f32_e32 v27, v27, v248
	v_mul_f32_e32 v28, v28, v248
	v_mul_f32_e32 v29, v29, v248
	v_mul_f32_e32 v30, v30, v248
	v_mul_f32_e32 v31, v31, v248
	v_mul_f32_e32 v32, v32, v248
	v_mul_f32_e32 v33, v33, v248
	v_mul_f32_e32 v2, v2, v248
	v_mul_f32_e32 v3, v3, v248
	v_mul_f32_e32 v4, v4, v248
	v_mul_f32_e32 v5, v5, v248
	v_mul_f32_e32 v6, v6, v248
	v_mul_f32_e32 v7, v7, v248
	v_mul_f32_e32 v8, v8, v248
	v_mul_f32_e32 v9, v9, v248
	v_mul_f32_e32 v10, v10, v248
	v_mul_f32_e32 v11, v11, v248
	v_mul_f32_e32 v12, v12, v248
	v_mul_f32_e32 v13, v13, v248
	v_mul_f32_e32 v14, v14, v248
	v_mul_f32_e32 v15, v15, v248
	v_mul_f32_e32 v16, v16, v248
	v_mul_f32_e32 v17, v17, v248
	v_mul_f32_e32 v50, v50, v248
	v_mul_f32_e32 v51, v51, v248
	v_mul_f32_e32 v52, v52, v248
	v_mul_f32_e32 v53, v53, v248
	v_mul_f32_e32 v54, v54, v248
	v_mul_f32_e32 v55, v55, v248
	v_mul_f32_e32 v56, v56, v248
	v_mul_f32_e32 v57, v57, v248
	v_mul_f32_e32 v58, v58, v248
	v_mul_f32_e32 v59, v59, v248
	v_mul_f32_e32 v60, v60, v248
	v_mul_f32_e32 v61, v61, v248
	v_mul_f32_e32 v62, v62, v248
	v_mul_f32_e32 v63, v63, v248
	v_mul_f32_e32 v64, v64, v248
	v_mul_f32_e32 v65, v65, v248
	s_branch .Lat_post_0
.Lat_rare_1:
	s_nop 1
	v_cndmask_b32_e32 v179, 0, v178, vcc
	v_sub_f32_e32 v66, v66, v179
	v_exp_f32_e64 v248, -v179
	v_sub_f32_e32 v98, v98, v179
	v_sub_f32_e32 v99, v99, v179
	v_sub_f32_e32 v100, v100, v179
	v_sub_f32_e32 v101, v101, v179
	v_sub_f32_e32 v102, v102, v179
	v_sub_f32_e32 v103, v103, v179
	v_sub_f32_e32 v104, v104, v179
	v_sub_f32_e32 v105, v105, v179
	v_sub_f32_e32 v106, v106, v179
	v_sub_f32_e32 v107, v107, v179
	v_sub_f32_e32 v108, v108, v179
	v_sub_f32_e32 v109, v109, v179
	v_sub_f32_e32 v110, v110, v179
	v_sub_f32_e32 v111, v111, v179
	v_sub_f32_e32 v112, v112, v179
	v_sub_f32_e32 v113, v113, v179
	v_sub_f32_e32 v82, v82, v179
	v_sub_f32_e32 v83, v83, v179
	v_sub_f32_e32 v84, v84, v179
	v_sub_f32_e32 v85, v85, v179
	v_sub_f32_e32 v86, v86, v179
	v_sub_f32_e32 v87, v87, v179
	v_sub_f32_e32 v88, v88, v179
	v_sub_f32_e32 v89, v89, v179
	v_sub_f32_e32 v90, v90, v179
	v_sub_f32_e32 v91, v91, v179
	v_sub_f32_e32 v92, v92, v179
	v_sub_f32_e32 v93, v93, v179
	v_sub_f32_e32 v94, v94, v179
	v_sub_f32_e32 v95, v95, v179
	v_sub_f32_e32 v96, v96, v179
	v_sub_f32_e32 v97, v97, v179
	v_mov_b32_e32 v67, v66
	v_mov_b32_e32 v68, v66
	v_mov_b32_e32 v69, v66
	v_mov_b32_e32 v70, v66
	v_mov_b32_e32 v71, v66
	v_mov_b32_e32 v72, v66
	v_mov_b32_e32 v73, v66
	v_mov_b32_e32 v74, v66
	v_mov_b32_e32 v75, v66
	v_mov_b32_e32 v76, v66
	v_mov_b32_e32 v77, v66
	v_mov_b32_e32 v78, v66
	v_mov_b32_e32 v79, v66
	v_mov_b32_e32 v80, v66
	v_mov_b32_e32 v81, v66
	v_mul_f32_e32 v197, v197, v248
	v_mul_f32_e32 v207, v207, v248
	v_mul_f32_e32 v34, v34, v248
	v_mul_f32_e32 v35, v35, v248
	v_mul_f32_e32 v36, v36, v248
	v_mul_f32_e32 v37, v37, v248
	v_mul_f32_e32 v38, v38, v248
	v_mul_f32_e32 v39, v39, v248
	v_mul_f32_e32 v40, v40, v248
	v_mul_f32_e32 v41, v41, v248
	v_mul_f32_e32 v42, v42, v248
	v_mul_f32_e32 v43, v43, v248
	v_mul_f32_e32 v44, v44, v248
	v_mul_f32_e32 v45, v45, v248
	v_mul_f32_e32 v46, v46, v248
	v_mul_f32_e32 v47, v47, v248
	v_mul_f32_e32 v48, v48, v248
	v_mul_f32_e32 v49, v49, v248
	v_mul_f32_e32 v18, v18, v248
	v_mul_f32_e32 v19, v19, v248
	v_mul_f32_e32 v20, v20, v248
	v_mul_f32_e32 v21, v21, v248
	v_mul_f32_e32 v22, v22, v248
	v_mul_f32_e32 v23, v23, v248
	v_mul_f32_e32 v24, v24, v248
	v_mul_f32_e32 v25, v25, v248
	v_mul_f32_e32 v26, v26, v248
	v_mul_f32_e32 v27, v27, v248
	v_mul_f32_e32 v28, v28, v248
	v_mul_f32_e32 v29, v29, v248
	v_mul_f32_e32 v30, v30, v248
	v_mul_f32_e32 v31, v31, v248
	v_mul_f32_e32 v32, v32, v248
	v_mul_f32_e32 v33, v33, v248
	v_mul_f32_e32 v2, v2, v248
	v_mul_f32_e32 v3, v3, v248
	v_mul_f32_e32 v4, v4, v248
	v_mul_f32_e32 v5, v5, v248
	v_mul_f32_e32 v6, v6, v248
	v_mul_f32_e32 v7, v7, v248
	v_mul_f32_e32 v8, v8, v248
	v_mul_f32_e32 v9, v9, v248
	v_mul_f32_e32 v10, v10, v248
	v_mul_f32_e32 v11, v11, v248
	v_mul_f32_e32 v12, v12, v248
	v_mul_f32_e32 v13, v13, v248
	v_mul_f32_e32 v14, v14, v248
	v_mul_f32_e32 v15, v15, v248
	v_mul_f32_e32 v16, v16, v248
	v_mul_f32_e32 v17, v17, v248
	v_mul_f32_e32 v50, v50, v248
	v_mul_f32_e32 v51, v51, v248
	v_mul_f32_e32 v52, v52, v248
	v_mul_f32_e32 v53, v53, v248
	v_mul_f32_e32 v54, v54, v248
	v_mul_f32_e32 v55, v55, v248
	v_mul_f32_e32 v56, v56, v248
	v_mul_f32_e32 v57, v57, v248
	v_mul_f32_e32 v58, v58, v248
	v_mul_f32_e32 v59, v59, v248
	v_mul_f32_e32 v60, v60, v248
	v_mul_f32_e32 v61, v61, v248
	v_mul_f32_e32 v62, v62, v248
	v_mul_f32_e32 v63, v63, v248
	v_mul_f32_e32 v64, v64, v248
	v_mul_f32_e32 v65, v65, v248
	s_branch .Lat_post_1
; DI float ex2(float x) { return __builtin_amdgcn_exp2f(x); }
; DI void attn_block(const Params& p, int layer, int hd, int q0, int nkeys, char* smem) {
;     ...
;     if (__any(mx > m + 8.f)) {
;       const float mn = (mx > m + 8.f) ? mx : m;
;       const float alpha = ex2(m - mn);
;       l *= alpha;
; #pragma unroll
;       for (int vt = 0; vt < 4; ++vt)
; #pragma unroll
;         for (int i = 0; i < 16; ++i) o[vt][i] *= alpha;
;       m = mn;
;     }
;     ...
;     l += (ls[0] + ls[1]) + (ls[2] + ls[3]);
;     __syncthreads();
;     sc[0] = sn[0]; sc[1] = sn[1];
;     { const int tmp = c0; c0 = c1; c1 = c2; c2 = tmp; }
;   }
;     ...
;   l += __shfl_xor(l, 32);
.Lat_rare_2:
	s_nop 1
	v_cndmask_b32_e32 v179, 0, v178, vcc
	v_sub_f32_e32 v66, v66, v179
	v_exp_f32_e64 v248, -v179
	v_sub_f32_e32 v114, v114, v179
	v_sub_f32_e32 v115, v115, v179
	v_sub_f32_e32 v116, v116, v179
	v_sub_f32_e32 v117, v117, v179
	v_sub_f32_e32 v118, v118, v179
	v_sub_f32_e32 v119, v119, v179
	v_sub_f32_e32 v120, v120, v179
	v_sub_f32_e32 v121, v121, v179
	v_sub_f32_e32 v122, v122, v179
	v_sub_f32_e32 v123, v123, v179
	v_sub_f32_e32 v124, v124, v179
	v_sub_f32_e32 v125, v125, v179
	v_sub_f32_e32 v126, v126, v179
	v_sub_f32_e32 v127, v127, v179
	v_sub_f32_e32 v128, v128, v179
	v_sub_f32_e32 v129, v129, v179
	v_sub_f32_e32 v98, v98, v179
	v_sub_f32_e32 v99, v99, v179
	v_sub_f32_e32 v100, v100, v179
	v_sub_f32_e32 v101, v101, v179
	v_sub_f32_e32 v102, v102, v179
	v_sub_f32_e32 v103, v103, v179
	v_sub_f32_e32 v104, v104, v179
	v_sub_f32_e32 v105, v105, v179
	v_sub_f32_e32 v106, v106, v179
	v_sub_f32_e32 v107, v107, v179
	v_sub_f32_e32 v108, v108, v179
	v_sub_f32_e32 v109, v109, v179
	v_sub_f32_e32 v110, v110, v179
	v_sub_f32_e32 v111, v111, v179
	v_sub_f32_e32 v112, v112, v179
	v_sub_f32_e32 v113, v113, v179
	v_mov_b32_e32 v67, v66
	v_mov_b32_e32 v68, v66
	v_mov_b32_e32 v69, v66
	v_mov_b32_e32 v70, v66
	v_mov_b32_e32 v71, v66
	v_mov_b32_e32 v72, v66
	v_mov_b32_e32 v73, v66
	v_mov_b32_e32 v74, v66
	v_mov_b32_e32 v75, v66
	v_mov_b32_e32 v76, v66
	v_mov_b32_e32 v77, v66
	v_mov_b32_e32 v78, v66
	v_mov_b32_e32 v79, v66
	v_mov_b32_e32 v80, v66
	v_mov_b32_e32 v81, v66
	v_mul_f32_e32 v197, v197, v248
	v_mul_f32_e32 v207, v207, v248
	v_mul_f32_e32 v34, v34, v248
	v_mul_f32_e32 v35, v35, v248
	v_mul_f32_e32 v36, v36, v248
	v_mul_f32_e32 v37, v37, v248
	v_mul_f32_e32 v38, v38, v248
	v_mul_f32_e32 v39, v39, v248
	v_mul_f32_e32 v40, v40, v248
	v_mul_f32_e32 v41, v41, v248
	v_mul_f32_e32 v42, v42, v248
	v_mul_f32_e32 v43, v43, v248
	v_mul_f32_e32 v44, v44, v248
	v_mul_f32_e32 v45, v45, v248
	v_mul_f32_e32 v46, v46, v248
	v_mul_f32_e32 v47, v47, v248
	v_mul_f32_e32 v48, v48, v248
	v_mul_f32_e32 v49, v49, v248
	v_mul_f32_e32 v18, v18, v248
	v_mul_f32_e32 v19, v19, v248
	v_mul_f32_e32 v20, v20, v248
	v_mul_f32_e32 v21, v21, v248
	v_mul_f32_e32 v22, v22, v248
	v_mul_f32_e32 v23, v23, v248
	v_mul_f32_e32 v24, v24, v248
	v_mul_f32_e32 v25, v25, v248
	v_mul_f32_e32 v26, v26, v248
	v_mul_f32_e32 v27, v27, v248
	v_mul_f32_e32 v28, v28, v248
	v_mul_f32_e32 v29, v29, v248
	v_mul_f32_e32 v30, v30, v248
	v_mul_f32_e32 v31, v31, v248
	v_mul_f32_e32 v32, v32, v248
	v_mul_f32_e32 v33, v33, v248
	v_mul_f32_e32 v2, v2, v248
	v_mul_f32_e32 v3, v3, v248
	v_mul_f32_e32 v4, v4, v248
	v_mul_f32_e32 v5, v5, v248
	v_mul_f32_e32 v6, v6, v248
	v_mul_f32_e32 v7, v7, v248
	v_mul_f32_e32 v8, v8, v248
	v_mul_f32_e32 v9, v9, v248
	v_mul_f32_e32 v10, v10, v248
	v_mul_f32_e32 v11, v11, v248
	v_mul_f32_e32 v12, v12, v248
	v_mul_f32_e32 v13, v13, v248
	v_mul_f32_e32 v14, v14, v248
	v_mul_f32_e32 v15, v15, v248
	v_mul_f32_e32 v16, v16, v248
	v_mul_f32_e32 v17, v17, v248
	v_mul_f32_e32 v50, v50, v248
	v_mul_f32_e32 v51, v51, v248
	v_mul_f32_e32 v52, v52, v248
	v_mul_f32_e32 v53, v53, v248
	v_mul_f32_e32 v54, v54, v248
	v_mul_f32_e32 v55, v55, v248
	v_mul_f32_e32 v56, v56, v248
	v_mul_f32_e32 v57, v57, v248
	v_mul_f32_e32 v58, v58, v248
	v_mul_f32_e32 v59, v59, v248
	v_mul_f32_e32 v60, v60, v248
	v_mul_f32_e32 v61, v61, v248
	v_mul_f32_e32 v62, v62, v248
	v_mul_f32_e32 v63, v63, v248
	v_mul_f32_e32 v64, v64, v248
	v_mul_f32_e32 v65, v65, v248
	s_branch .Lat_post_2
.Lat_exit:
	s_waitcnt vmcnt(0)
	s_waitcnt lgkmcnt(0)
	v_mov_b64_e32 v[66:67], v[82:83]
	v_mov_b64_e32 v[68:69], v[84:85]
	v_mov_b64_e32 v[70:71], v[86:87]
	v_mov_b64_e32 v[72:73], v[88:89]
	v_mov_b64_e32 v[74:75], v[90:91]
	v_mov_b64_e32 v[76:77], v[92:93]
	v_mov_b64_e32 v[78:79], v[94:95]
	v_mov_b64_e32 v[80:81], v[96:97]
	v_mov_b64_e32 v[82:83], v[98:99]
	v_mov_b64_e32 v[84:85], v[100:101]
	v_mov_b64_e32 v[86:87], v[102:103]
	v_mov_b64_e32 v[88:89], v[104:105]
	v_mov_b64_e32 v[90:91], v[106:107]
	v_mov_b64_e32 v[92:93], v[108:109]
	v_mov_b64_e32 v[94:95], v[110:111]
	v_mov_b64_e32 v[96:97], v[112:113]
	v_add_f32_e32 v195, v197, v207
	v_mov_b32_e32 v204, 0
	v_mov_b32_e32 v196, 0x1a410
	v_lshl_add_u32 v196, v0, 2, v196
	ds_read_b32 v170, v196 offset:0
	ds_read_b32 v171, v196 offset:2048
	ds_read_b32 v172, v196 offset:4096
	ds_read_b32 v173, v196 offset:6144
	ds_read_b32 v174, v196 offset:8192
	ds_read_b32 v175, v196 offset:10240
	ds_read_b32 v176, v196 offset:12288
	ds_read_b32 v177, v196 offset:14336
	s_waitcnt lgkmcnt(0)
	ds_read_b32 v178, v196 offset:16384
	ds_read_b32 v179, v196 offset:18432
	s_mov_b32 s7, 1
	s_mov_b32 s42, 2
	s_mov_b32 s4, 0x11800
	s_mov_b32 s8, 0x8c10
	s_movk_i32 s6, 0x83
	s_waitcnt lgkmcnt(0)
	s_branch .LBB0_400
